# v43 + softmax row-sum via v_pk_add_f32 (in-place exps, 16 packed adds instead of 32 scalar adds per key tile)
# baseline (speedup 1.0000x reference)
.LBB0_915:
	v_cvt_pk_bf16_f32 v166, v84, v85
	v_cvt_pk_bf16_f32 v167, v86, v87
	v_cvt_pk_bf16_f32 v168, v88, v89
	v_cvt_pk_bf16_f32 v169, v90, v91
	v_cvt_pk_bf16_f32 v86, v92, v93
	v_cvt_pk_bf16_f32 v87, v94, v95
	v_cvt_pk_bf16_f32 v88, v96, v97
	v_cvt_pk_bf16_f32 v89, v98, v99
	v_cvt_pk_bf16_f32 v68, v68, v69
	v_cvt_pk_bf16_f32 v69, v70, v71
	v_cvt_pk_bf16_f32 v70, v72, v73
	v_cvt_pk_bf16_f32 v71, v74, v75
	v_cvt_pk_bf16_f32 v72, v76, v77
	v_cvt_pk_bf16_f32 v73, v78, v79
	v_cvt_pk_bf16_f32 v74, v80, v81
	v_cvt_pk_bf16_f32 v75, v82, v83
	s_waitcnt lgkmcnt(0)
	v_add_f32_e32 v99, v241, v242
	v_fmac_f32_e32 v99, v161, v163
	v_mfma_f32_32x32x16_bf16 v[52:67], v[166:169], v[144:147], v[52:67]
	v_mfma_f32_32x32x16_bf16 v[52:67], v[86:89], v[140:143], v[52:67]
	v_mfma_f32_32x32x16_bf16 v[52:67], v[68:71], v[136:139], v[52:67]
	v_mfma_f32_32x32x16_bf16 v[52:67], v[72:75], v[132:135], v[52:67]
	ds_read_b64_tr_b16 v[76:77], v162 offset:0x400
	ds_read_b64_tr_b16 v[78:79], v162 offset:0xc00
	ds_read_b64_tr_b16 v[80:81], v162 offset:0x1400
	ds_read_b64_tr_b16 v[82:83], v162 offset:0x1c00
	ds_read_b64_tr_b16 v[90:91], v162 offset:0x2400
	ds_read_b64_tr_b16 v[92:93], v162 offset:0x2c00
	ds_read_b64_tr_b16 v[94:95], v162 offset:0x3400
	ds_read_b64_tr_b16 v[96:97], v162 offset:0x3c00
	v_mfma_f32_32x32x16_bf16 v[36:51], v[166:169], v[128:131], v[36:51]
	v_mfma_f32_32x32x16_bf16 v[36:51], v[86:89], v[124:127], v[36:51]
	v_mfma_f32_32x32x16_bf16 v[36:51], v[68:71], v[120:123], v[36:51]
	v_mfma_f32_32x32x16_bf16 v[36:51], v[72:75], v[116:119], v[36:51]
	ds_read_b64_tr_b16 v[116:117], v162 offset:0x600
	ds_read_b64_tr_b16 v[118:119], v162 offset:0xe00
	ds_read_b64_tr_b16 v[120:121], v162 offset:0x1600
	ds_read_b64_tr_b16 v[122:123], v162 offset:0x1e00
	ds_read_b64_tr_b16 v[124:125], v162 offset:0x2600
	ds_read_b64_tr_b16 v[126:127], v162 offset:0x2e00
	ds_read_b64_tr_b16 v[128:129], v162 offset:0x3600
	ds_read_b64_tr_b16 v[130:131], v162 offset:0x3e00
	s_waitcnt lgkmcnt(8)
	v_mfma_f32_32x32x16_bf16 v[20:35], v[166:169], v[76:79], v[20:35]
	v_mfma_f32_32x32x16_bf16 v[20:35], v[86:89], v[80:83], v[20:35]
	v_mfma_f32_32x32x16_bf16 v[20:35], v[68:71], v[90:93], v[20:35]
	v_mfma_f32_32x32x16_bf16 v[20:35], v[72:75], v[94:97], v[20:35]
	s_waitcnt lgkmcnt(0)
	v_mfma_f32_32x32x16_bf16 v[4:19], v[166:169], v[116:119], v[4:19]
	v_mov_b32_e32 v161, v99
	v_mfma_f32_32x32x16_bf16 v[4:19], v[86:89], v[120:123], v[4:19]
	v_mfma_f32_32x32x16_bf16 v[4:19], v[68:71], v[124:127], v[4:19]
	v_mfma_f32_32x32x16_bf16 v[4:19], v[72:75], v[128:131], v[4:19]

.LBB0_924:
	v_exp_f32_e32 v84, v84
	v_exp_f32_e32 v85, v85
	v_exp_f32_e32 v86, v86
	v_exp_f32_e32 v87, v87
	v_exp_f32_e32 v88, v88
	v_exp_f32_e32 v89, v89
	v_exp_f32_e32 v90, v90
	v_exp_f32_e32 v91, v91
	v_exp_f32_e32 v92, v92
	v_exp_f32_e32 v93, v93
	v_exp_f32_e32 v94, v94
	v_exp_f32_e32 v95, v95
	v_exp_f32_e32 v96, v96
	v_exp_f32_e32 v97, v97
	v_exp_f32_e32 v98, v98
	v_exp_f32_e32 v99, v99
	v_exp_f32_e32 v68, v68
	v_exp_f32_e32 v69, v69
	v_pk_add_f32 v[242:243], v[84:85], v[86:87]
	v_exp_f32_e32 v70, v70
	v_exp_f32_e32 v71, v71
	v_pk_add_f32 v[242:243], v[242:243], v[88:89]
	v_exp_f32_e32 v72, v72
	v_exp_f32_e32 v73, v73
	v_pk_add_f32 v[242:243], v[242:243], v[90:91]
	v_exp_f32_e32 v74, v74
	v_exp_f32_e32 v75, v75
	v_pk_add_f32 v[242:243], v[242:243], v[92:93]
	v_exp_f32_e32 v76, v76
	v_exp_f32_e32 v77, v77
	v_pk_add_f32 v[242:243], v[242:243], v[94:95]
	v_exp_f32_e32 v78, v78
	v_exp_f32_e32 v79, v79
	v_pk_add_f32 v[242:243], v[242:243], v[96:97]
	v_exp_f32_e32 v80, v80
	v_exp_f32_e32 v81, v81
	v_pk_add_f32 v[242:243], v[242:243], v[98:99]
	v_exp_f32_e32 v82, v82
	v_exp_f32_e32 v83, v83
	v_pk_add_f32 v[242:243], v[242:243], v[68:69]
	v_pk_add_f32 v[242:243], v[242:243], v[70:71]
	v_pk_add_f32 v[242:243], v[242:243], v[72:73]
	v_pk_add_f32 v[242:243], v[242:243], v[74:75]
	v_pk_add_f32 v[242:243], v[242:243], v[76:77]
	v_pk_add_f32 v[242:243], v[242:243], v[78:79]
	v_pk_add_f32 v[242:243], v[242:243], v[80:81]
	v_pk_add_f32 v[242:243], v[242:243], v[82:83]
	v_add_f32_e32 v241, v242, v243
	v_mov_b32_e32 v242, v241
	s_nop 1
	v_permlane32_swap_b32_e32 v241, v242
	v_cmp_gt_f32_e32 vcc, 1.0, v163
	s_cbranch_vccz .LBB0_928
	s_and_saveexec_b64 s[12:13], s[10:11]
	ds_write_b32 v154, v163 offset:128
	s_or_b64 exec, exec, s[12:13]
	s_waitcnt lgkmcnt(0)
	v_add_u32_e32 v178, s95, v2
	ds_read_b128 v[166:169], v178 offset:224
	ds_read_b128 v[170:173], v178 offset:192
	ds_read_b128 v[174:177], v178 offset:160
	ds_read_b128 v[178:181], v178 offset:128
	s_waitcnt lgkmcnt(0)
	s_waitcnt lgkmcnt(0)
	v_pk_mul_f32 v[64:65], v[166:167], v[64:65]
	v_pk_mul_f32 v[60:61], v[170:171], v[60:61]
	v_pk_mul_f32 v[56:57], v[174:175], v[56:57]
	v_pk_mul_f32 v[66:67], v[168:169], v[66:67]
	v_pk_mul_f32 v[62:63], v[172:173], v[62:63]
	v_pk_mul_f32 v[58:59], v[176:177], v[58:59]
	v_pk_mul_f32 v[54:55], v[180:181], v[54:55]
	v_pk_mul_f32 v[52:53], v[178:179], v[52:53]
	v_pk_mul_f32 v[48:49], v[166:167], v[48:49]
	v_pk_mul_f32 v[44:45], v[170:171], v[44:45]
	v_pk_mul_f32 v[40:41], v[174:175], v[40:41]
	v_pk_mul_f32 v[50:51], v[168:169], v[50:51]
	v_pk_mul_f32 v[46:47], v[172:173], v[46:47]
	v_pk_mul_f32 v[42:43], v[176:177], v[42:43]
	v_pk_mul_f32 v[38:39], v[180:181], v[38:39]
	v_pk_mul_f32 v[36:37], v[178:179], v[36:37]
	v_pk_mul_f32 v[32:33], v[166:167], v[32:33]
	v_pk_mul_f32 v[28:29], v[170:171], v[28:29]
	v_pk_mul_f32 v[24:25], v[174:175], v[24:25]
	v_pk_mul_f32 v[34:35], v[168:169], v[34:35]
	v_pk_mul_f32 v[30:31], v[172:173], v[30:31]
	v_pk_mul_f32 v[26:27], v[176:177], v[26:27]
	v_pk_mul_f32 v[22:23], v[180:181], v[22:23]
	v_pk_mul_f32 v[20:21], v[178:179], v[20:21]
	v_pk_mul_f32 v[16:17], v[166:167], v[16:17]
	v_pk_mul_f32 v[12:13], v[170:171], v[12:13]
	v_pk_mul_f32 v[8:9], v[174:175], v[8:9]
	v_pk_mul_f32 v[18:19], v[168:169], v[18:19]
	v_pk_mul_f32 v[14:15], v[172:173], v[14:15]
	v_pk_mul_f32 v[10:11], v[176:177], v[10:11]
	v_pk_mul_f32 v[6:7], v[180:181], v[6:7]
	v_pk_mul_f32 v[4:5], v[178:179], v[4:5]
.LBB0_928:
	v_cvt_pk_bf16_f32 v166, v84, v85
	v_cvt_pk_bf16_f32 v167, v86, v87
	v_cvt_pk_bf16_f32 v168, v88, v89
	v_cvt_pk_bf16_f32 v169, v90, v91
	v_cvt_pk_bf16_f32 v86, v92, v93
	v_cvt_pk_bf16_f32 v87, v94, v95
	v_cvt_pk_bf16_f32 v88, v96, v97
	v_cvt_pk_bf16_f32 v89, v98, v99
	v_cvt_pk_bf16_f32 v68, v68, v69
	v_cvt_pk_bf16_f32 v69, v70, v71
	v_cvt_pk_bf16_f32 v70, v72, v73
	v_cvt_pk_bf16_f32 v71, v74, v75
	v_cvt_pk_bf16_f32 v72, v76, v77
	v_cvt_pk_bf16_f32 v73, v78, v79
	v_cvt_pk_bf16_f32 v74, v80, v81
	v_cvt_pk_bf16_f32 v75, v82, v83
	s_waitcnt lgkmcnt(0)
	v_add_f32_e32 v99, v241, v242
	v_fmac_f32_e32 v99, v161, v163
	v_mfma_f32_32x32x16_bf16 v[52:67], v[166:169], v[144:147], v[52:67]
	v_mfma_f32_32x32x16_bf16 v[52:67], v[86:89], v[140:143], v[52:67]
	v_mfma_f32_32x32x16_bf16 v[52:67], v[68:71], v[136:139], v[52:67]
	v_mfma_f32_32x32x16_bf16 v[52:67], v[72:75], v[132:135], v[52:67]
	ds_read_b64_tr_b16 v[76:77], v162 offset:0x400
	ds_read_b64_tr_b16 v[78:79], v162 offset:0xc00
	ds_read_b64_tr_b16 v[80:81], v162 offset:0x1400
	ds_read_b64_tr_b16 v[82:83], v162 offset:0x1c00
	ds_read_b64_tr_b16 v[90:91], v162 offset:0x2400
	ds_read_b64_tr_b16 v[92:93], v162 offset:0x2c00
	ds_read_b64_tr_b16 v[94:95], v162 offset:0x3400
	ds_read_b64_tr_b16 v[96:97], v162 offset:0x3c00
	v_mfma_f32_32x32x16_bf16 v[36:51], v[166:169], v[128:131], v[36:51]
	v_mfma_f32_32x32x16_bf16 v[36:51], v[86:89], v[124:127], v[36:51]
	v_mfma_f32_32x32x16_bf16 v[36:51], v[68:71], v[120:123], v[36:51]
	v_mfma_f32_32x32x16_bf16 v[36:51], v[72:75], v[116:119], v[36:51]
	ds_read_b64_tr_b16 v[116:117], v162 offset:0x600
	ds_read_b64_tr_b16 v[118:119], v162 offset:0xe00
	ds_read_b64_tr_b16 v[120:121], v162 offset:0x1600
	ds_read_b64_tr_b16 v[122:123], v162 offset:0x1e00
	ds_read_b64_tr_b16 v[124:125], v162 offset:0x2600
	ds_read_b64_tr_b16 v[126:127], v162 offset:0x2e00
	ds_read_b64_tr_b16 v[128:129], v162 offset:0x3600
	ds_read_b64_tr_b16 v[130:131], v162 offset:0x3e00
	s_waitcnt lgkmcnt(8)
	v_mfma_f32_32x32x16_bf16 v[20:35], v[166:169], v[76:79], v[20:35]
	v_mfma_f32_32x32x16_bf16 v[20:35], v[86:89], v[80:83], v[20:35]
	v_mfma_f32_32x32x16_bf16 v[20:35], v[68:71], v[90:93], v[20:35]
	v_mfma_f32_32x32x16_bf16 v[20:35], v[72:75], v[94:97], v[20:35]
	s_waitcnt lgkmcnt(0)
	v_mfma_f32_32x32x16_bf16 v[4:19], v[166:169], v[116:119], v[4:19]
	v_mov_b32_e32 v161, v99
	v_mfma_f32_32x32x16_bf16 v[4:19], v[86:89], v[120:123], v[4:19]
	v_mfma_f32_32x32x16_bf16 v[4:19], v[68:71], v[124:127], v[4:19]
	v_mfma_f32_32x32x16_bf16 v[4:19], v[72:75], v[128:131], v[4:19]
	s_add_i32 s3, s2, 0x80
	s_cmp_gt_i32 s3, s90
	s_cbranch_scc1 .LBB0_916

.LBB0_932:
	v_exp_f32_e32 v84, v84
	v_exp_f32_e32 v85, v85
	v_exp_f32_e32 v86, v86
	v_exp_f32_e32 v87, v87
	v_exp_f32_e32 v88, v88
	v_exp_f32_e32 v89, v89
	v_exp_f32_e32 v90, v90
	v_exp_f32_e32 v91, v91
	v_exp_f32_e32 v92, v92
	v_exp_f32_e32 v93, v93
	v_exp_f32_e32 v94, v94
	v_exp_f32_e32 v95, v95
	v_exp_f32_e32 v96, v96
	v_exp_f32_e32 v97, v97
	v_exp_f32_e32 v98, v98
	v_exp_f32_e32 v99, v99
	v_exp_f32_e32 v68, v68
	v_exp_f32_e32 v69, v69
	v_pk_add_f32 v[242:243], v[84:85], v[86:87]
	v_exp_f32_e32 v70, v70
	v_exp_f32_e32 v71, v71
	v_pk_add_f32 v[242:243], v[242:243], v[88:89]
	v_exp_f32_e32 v72, v72
	v_exp_f32_e32 v73, v73
	v_pk_add_f32 v[242:243], v[242:243], v[90:91]
	v_exp_f32_e32 v74, v74
	v_exp_f32_e32 v75, v75
	v_pk_add_f32 v[242:243], v[242:243], v[92:93]
	v_exp_f32_e32 v76, v76
	v_exp_f32_e32 v77, v77
	v_pk_add_f32 v[242:243], v[242:243], v[94:95]
	v_exp_f32_e32 v78, v78
	v_exp_f32_e32 v79, v79
	v_pk_add_f32 v[242:243], v[242:243], v[96:97]
	v_exp_f32_e32 v80, v80
	v_exp_f32_e32 v81, v81
	v_pk_add_f32 v[242:243], v[242:243], v[98:99]
	v_exp_f32_e32 v82, v82
	v_exp_f32_e32 v83, v83
	v_pk_add_f32 v[242:243], v[242:243], v[68:69]
	v_pk_add_f32 v[242:243], v[242:243], v[70:71]
	v_pk_add_f32 v[242:243], v[242:243], v[72:73]
	v_pk_add_f32 v[242:243], v[242:243], v[74:75]
	v_pk_add_f32 v[242:243], v[242:243], v[76:77]
	v_pk_add_f32 v[242:243], v[242:243], v[78:79]
	v_pk_add_f32 v[242:243], v[242:243], v[80:81]
	v_pk_add_f32 v[242:243], v[242:243], v[82:83]
	v_add_f32_e32 v241, v242, v243
	v_mov_b32_e32 v242, v241
	s_nop 1
	v_permlane32_swap_b32_e32 v241, v242
	v_cmp_gt_f32_e32 vcc, 1.0, v163
	s_cbranch_vccz .LBB0_915
	s_and_saveexec_b64 s[12:13], s[10:11]
	s_cbranch_execz .LBB0_914
	ds_write_b32 v154, v163 offset:128
	s_branch .LBB0_914

.LBB0_941:
	v_cvt_pk_bf16_f32 v168, v84, v85
	v_cvt_pk_bf16_f32 v169, v86, v87
	v_cvt_pk_bf16_f32 v170, v88, v89
	v_cvt_pk_bf16_f32 v171, v90, v91
	v_cvt_pk_bf16_f32 v86, v92, v93
	v_cvt_pk_bf16_f32 v87, v94, v95
	v_cvt_pk_bf16_f32 v88, v96, v97
	v_cvt_pk_bf16_f32 v89, v98, v99
	v_cvt_pk_bf16_f32 v68, v68, v69
	v_cvt_pk_bf16_f32 v69, v70, v71
	v_cvt_pk_bf16_f32 v70, v72, v73
	v_cvt_pk_bf16_f32 v71, v74, v75
	v_cvt_pk_bf16_f32 v72, v76, v77
	v_cvt_pk_bf16_f32 v73, v78, v79
	v_cvt_pk_bf16_f32 v74, v80, v81
	v_cvt_pk_bf16_f32 v75, v82, v83
	s_waitcnt lgkmcnt(0)
	v_add_f32_e32 v99, v241, v242
	v_fmac_f32_e32 v99, v163, v165
	v_mfma_f32_32x32x16_bf16 v[52:67], v[168:171], v[144:147], v[52:67]
	v_mfma_f32_32x32x16_bf16 v[52:67], v[86:89], v[140:143], v[52:67]
	v_mfma_f32_32x32x16_bf16 v[52:67], v[68:71], v[136:139], v[52:67]
	v_mfma_f32_32x32x16_bf16 v[52:67], v[72:75], v[132:135], v[52:67]
	ds_read_b64_tr_b16 v[76:77], v164 offset:0x400
	ds_read_b64_tr_b16 v[78:79], v164 offset:0xc00
	ds_read_b64_tr_b16 v[80:81], v164 offset:0x1400
	ds_read_b64_tr_b16 v[82:83], v164 offset:0x1c00
	ds_read_b64_tr_b16 v[90:91], v164 offset:0x2400
	ds_read_b64_tr_b16 v[92:93], v164 offset:0x2c00
	ds_read_b64_tr_b16 v[94:95], v164 offset:0x3400
	ds_read_b64_tr_b16 v[96:97], v164 offset:0x3c00
	v_mfma_f32_32x32x16_bf16 v[36:51], v[168:171], v[128:131], v[36:51]
	v_mfma_f32_32x32x16_bf16 v[36:51], v[86:89], v[124:127], v[36:51]
	v_mfma_f32_32x32x16_bf16 v[36:51], v[68:71], v[120:123], v[36:51]
	v_mfma_f32_32x32x16_bf16 v[36:51], v[72:75], v[116:119], v[36:51]
	ds_read_b64_tr_b16 v[116:117], v164 offset:0x600
	ds_read_b64_tr_b16 v[118:119], v164 offset:0xe00
	ds_read_b64_tr_b16 v[120:121], v164 offset:0x1600
	ds_read_b64_tr_b16 v[122:123], v164 offset:0x1e00
	ds_read_b64_tr_b16 v[124:125], v164 offset:0x2600
	ds_read_b64_tr_b16 v[126:127], v164 offset:0x2e00
	ds_read_b64_tr_b16 v[128:129], v164 offset:0x3600
	ds_read_b64_tr_b16 v[130:131], v164 offset:0x3e00
	s_waitcnt lgkmcnt(8)
	v_mfma_f32_32x32x16_bf16 v[20:35], v[168:171], v[76:79], v[20:35]
	v_mfma_f32_32x32x16_bf16 v[20:35], v[86:89], v[80:83], v[20:35]
	v_mfma_f32_32x32x16_bf16 v[20:35], v[68:71], v[90:93], v[20:35]
	v_mfma_f32_32x32x16_bf16 v[20:35], v[72:75], v[94:97], v[20:35]
	s_waitcnt lgkmcnt(0)
	v_mfma_f32_32x32x16_bf16 v[4:19], v[168:171], v[116:119], v[4:19]
	v_mov_b32_e32 v163, v99
	v_mfma_f32_32x32x16_bf16 v[4:19], v[86:89], v[120:123], v[4:19]
	v_mfma_f32_32x32x16_bf16 v[4:19], v[68:71], v[124:127], v[4:19]
	v_mfma_f32_32x32x16_bf16 v[4:19], v[72:75], v[128:131], v[4:19]

.LBB0_950:
	v_exp_f32_e32 v84, v84
	v_exp_f32_e32 v85, v85
	v_exp_f32_e32 v86, v86
	v_exp_f32_e32 v87, v87
	v_exp_f32_e32 v88, v88
	v_exp_f32_e32 v89, v89
	v_exp_f32_e32 v90, v90
	v_exp_f32_e32 v91, v91
	v_exp_f32_e32 v92, v92
	v_exp_f32_e32 v93, v93
	v_exp_f32_e32 v94, v94
	v_exp_f32_e32 v95, v95
	v_exp_f32_e32 v96, v96
	v_exp_f32_e32 v97, v97
	v_exp_f32_e32 v98, v98
	v_exp_f32_e32 v99, v99
	v_exp_f32_e32 v68, v68
	v_exp_f32_e32 v69, v69
	v_pk_add_f32 v[242:243], v[84:85], v[86:87]
	v_exp_f32_e32 v70, v70
	v_exp_f32_e32 v71, v71
	v_pk_add_f32 v[242:243], v[242:243], v[88:89]
	v_exp_f32_e32 v72, v72
	v_exp_f32_e32 v73, v73
	v_pk_add_f32 v[242:243], v[242:243], v[90:91]
	v_exp_f32_e32 v74, v74
	v_exp_f32_e32 v75, v75
	v_pk_add_f32 v[242:243], v[242:243], v[92:93]
	v_exp_f32_e32 v76, v76
	v_exp_f32_e32 v77, v77
	v_pk_add_f32 v[242:243], v[242:243], v[94:95]
	v_exp_f32_e32 v78, v78
	v_exp_f32_e32 v79, v79
	v_pk_add_f32 v[242:243], v[242:243], v[96:97]
	v_exp_f32_e32 v80, v80
	v_exp_f32_e32 v81, v81
	v_pk_add_f32 v[242:243], v[242:243], v[98:99]
	v_exp_f32_e32 v82, v82
	v_exp_f32_e32 v83, v83
	v_pk_add_f32 v[242:243], v[242:243], v[68:69]
	v_pk_add_f32 v[242:243], v[242:243], v[70:71]
	v_pk_add_f32 v[242:243], v[242:243], v[72:73]
	v_pk_add_f32 v[242:243], v[242:243], v[74:75]
	v_pk_add_f32 v[242:243], v[242:243], v[76:77]
	v_pk_add_f32 v[242:243], v[242:243], v[78:79]
	v_pk_add_f32 v[242:243], v[242:243], v[80:81]
	v_pk_add_f32 v[242:243], v[242:243], v[82:83]
	v_add_f32_e32 v241, v242, v243
	v_mov_b32_e32 v242, v241
	s_nop 1
	v_permlane32_swap_b32_e32 v241, v242
	v_cmp_gt_f32_e32 vcc, 1.0, v165
	s_cbranch_vccz .LBB0_954
	s_and_saveexec_b64 s[12:13], s[10:11]
	ds_write_b32 v155, v165 offset:128
	s_or_b64 exec, exec, s[12:13]
	s_waitcnt lgkmcnt(0)
	v_add_u32_e32 v180, s78, v2
	ds_read_b128 v[168:171], v180 offset:224
	ds_read_b128 v[172:175], v180 offset:192
	ds_read_b128 v[176:179], v180 offset:160
	ds_read_b128 v[180:183], v180 offset:128
	s_waitcnt lgkmcnt(0)
	s_waitcnt lgkmcnt(0)
	v_pk_mul_f32 v[64:65], v[168:169], v[64:65]
	v_pk_mul_f32 v[60:61], v[172:173], v[60:61]
	v_pk_mul_f32 v[56:57], v[176:177], v[56:57]
	v_pk_mul_f32 v[66:67], v[170:171], v[66:67]
	v_pk_mul_f32 v[62:63], v[174:175], v[62:63]
	v_pk_mul_f32 v[58:59], v[178:179], v[58:59]
	v_pk_mul_f32 v[54:55], v[182:183], v[54:55]
	v_pk_mul_f32 v[52:53], v[180:181], v[52:53]
	v_pk_mul_f32 v[48:49], v[168:169], v[48:49]
	v_pk_mul_f32 v[44:45], v[172:173], v[44:45]
	v_pk_mul_f32 v[40:41], v[176:177], v[40:41]
	v_pk_mul_f32 v[50:51], v[170:171], v[50:51]
	v_pk_mul_f32 v[46:47], v[174:175], v[46:47]
	v_pk_mul_f32 v[42:43], v[178:179], v[42:43]
	v_pk_mul_f32 v[38:39], v[182:183], v[38:39]
	v_pk_mul_f32 v[36:37], v[180:181], v[36:37]
	v_pk_mul_f32 v[32:33], v[168:169], v[32:33]
	v_pk_mul_f32 v[28:29], v[172:173], v[28:29]
	v_pk_mul_f32 v[24:25], v[176:177], v[24:25]
	v_pk_mul_f32 v[34:35], v[170:171], v[34:35]
	v_pk_mul_f32 v[30:31], v[174:175], v[30:31]
	v_pk_mul_f32 v[26:27], v[178:179], v[26:27]
	v_pk_mul_f32 v[22:23], v[182:183], v[22:23]
	v_pk_mul_f32 v[20:21], v[180:181], v[20:21]
	v_pk_mul_f32 v[16:17], v[168:169], v[16:17]
	v_pk_mul_f32 v[12:13], v[172:173], v[12:13]
	v_pk_mul_f32 v[8:9], v[176:177], v[8:9]
	v_pk_mul_f32 v[18:19], v[170:171], v[18:19]
	v_pk_mul_f32 v[14:15], v[174:175], v[14:15]
	v_pk_mul_f32 v[10:11], v[178:179], v[10:11]
	v_pk_mul_f32 v[6:7], v[182:183], v[6:7]
	v_pk_mul_f32 v[4:5], v[180:181], v[4:5]
.LBB0_954:
	v_cvt_pk_bf16_f32 v168, v84, v85
	v_cvt_pk_bf16_f32 v169, v86, v87
	v_cvt_pk_bf16_f32 v170, v88, v89
	v_cvt_pk_bf16_f32 v171, v90, v91
	v_cvt_pk_bf16_f32 v86, v92, v93
	v_cvt_pk_bf16_f32 v87, v94, v95
	v_cvt_pk_bf16_f32 v88, v96, v97
	v_cvt_pk_bf16_f32 v89, v98, v99
	v_cvt_pk_bf16_f32 v68, v68, v69
	v_cvt_pk_bf16_f32 v69, v70, v71
	v_cvt_pk_bf16_f32 v70, v72, v73
	v_cvt_pk_bf16_f32 v71, v74, v75
	v_cvt_pk_bf16_f32 v72, v76, v77
	v_cvt_pk_bf16_f32 v73, v78, v79
	v_cvt_pk_bf16_f32 v74, v80, v81
	v_cvt_pk_bf16_f32 v75, v82, v83
	s_waitcnt lgkmcnt(0)
	v_add_f32_e32 v99, v241, v242
	v_fmac_f32_e32 v99, v163, v165
	v_mfma_f32_32x32x16_bf16 v[52:67], v[168:171], v[144:147], v[52:67]
	v_mfma_f32_32x32x16_bf16 v[52:67], v[86:89], v[140:143], v[52:67]
	v_mfma_f32_32x32x16_bf16 v[52:67], v[68:71], v[136:139], v[52:67]
	v_mfma_f32_32x32x16_bf16 v[52:67], v[72:75], v[132:135], v[52:67]
	ds_read_b64_tr_b16 v[76:77], v164 offset:0x400
	ds_read_b64_tr_b16 v[78:79], v164 offset:0xc00
	ds_read_b64_tr_b16 v[80:81], v164 offset:0x1400
	ds_read_b64_tr_b16 v[82:83], v164 offset:0x1c00
	ds_read_b64_tr_b16 v[90:91], v164 offset:0x2400
	ds_read_b64_tr_b16 v[92:93], v164 offset:0x2c00
	ds_read_b64_tr_b16 v[94:95], v164 offset:0x3400
	ds_read_b64_tr_b16 v[96:97], v164 offset:0x3c00
	v_mfma_f32_32x32x16_bf16 v[36:51], v[168:171], v[128:131], v[36:51]
	v_mfma_f32_32x32x16_bf16 v[36:51], v[86:89], v[124:127], v[36:51]
	v_mfma_f32_32x32x16_bf16 v[36:51], v[68:71], v[120:123], v[36:51]
	v_mfma_f32_32x32x16_bf16 v[36:51], v[72:75], v[116:119], v[36:51]
	ds_read_b64_tr_b16 v[116:117], v164 offset:0x600
	ds_read_b64_tr_b16 v[118:119], v164 offset:0xe00
	ds_read_b64_tr_b16 v[120:121], v164 offset:0x1600
	ds_read_b64_tr_b16 v[122:123], v164 offset:0x1e00
	ds_read_b64_tr_b16 v[124:125], v164 offset:0x2600
	ds_read_b64_tr_b16 v[126:127], v164 offset:0x2e00
	ds_read_b64_tr_b16 v[128:129], v164 offset:0x3600
	ds_read_b64_tr_b16 v[130:131], v164 offset:0x3e00
	s_waitcnt lgkmcnt(8)
	v_mfma_f32_32x32x16_bf16 v[20:35], v[168:171], v[76:79], v[20:35]
	v_mfma_f32_32x32x16_bf16 v[20:35], v[86:89], v[80:83], v[20:35]
	v_mfma_f32_32x32x16_bf16 v[20:35], v[68:71], v[90:93], v[20:35]
	v_mfma_f32_32x32x16_bf16 v[20:35], v[72:75], v[94:97], v[20:35]
	s_waitcnt lgkmcnt(0)
	v_mfma_f32_32x32x16_bf16 v[4:19], v[168:171], v[116:119], v[4:19]
	v_mov_b32_e32 v163, v99
	v_mfma_f32_32x32x16_bf16 v[4:19], v[86:89], v[120:123], v[4:19]
	v_mfma_f32_32x32x16_bf16 v[4:19], v[68:71], v[124:127], v[4:19]
	v_mfma_f32_32x32x16_bf16 v[4:19], v[72:75], v[128:131], v[4:19]
	s_add_i32 s3, s2, 0x80
	s_cmp_gt_i32 s3, s80
	s_cbranch_scc1 .LBB0_942

.LBB0_958:
	v_exp_f32_e32 v84, v84
	v_exp_f32_e32 v85, v85
	v_exp_f32_e32 v86, v86
	v_exp_f32_e32 v87, v87
	v_exp_f32_e32 v88, v88
	v_exp_f32_e32 v89, v89
	v_exp_f32_e32 v90, v90
	v_exp_f32_e32 v91, v91
	v_exp_f32_e32 v92, v92
	v_exp_f32_e32 v93, v93
	v_exp_f32_e32 v94, v94
	v_exp_f32_e32 v95, v95
	v_exp_f32_e32 v96, v96
	v_exp_f32_e32 v97, v97
	v_exp_f32_e32 v98, v98
	v_exp_f32_e32 v99, v99
	v_exp_f32_e32 v68, v68
	v_exp_f32_e32 v69, v69
	v_pk_add_f32 v[242:243], v[84:85], v[86:87]
	v_exp_f32_e32 v70, v70
	v_exp_f32_e32 v71, v71
	v_pk_add_f32 v[242:243], v[242:243], v[88:89]
	v_exp_f32_e32 v72, v72
	v_exp_f32_e32 v73, v73
	v_pk_add_f32 v[242:243], v[242:243], v[90:91]
	v_exp_f32_e32 v74, v74
	v_exp_f32_e32 v75, v75
	v_pk_add_f32 v[242:243], v[242:243], v[92:93]
	v_exp_f32_e32 v76, v76
	v_exp_f32_e32 v77, v77
	v_pk_add_f32 v[242:243], v[242:243], v[94:95]
	v_exp_f32_e32 v78, v78
	v_exp_f32_e32 v79, v79
	v_pk_add_f32 v[242:243], v[242:243], v[96:97]
	v_exp_f32_e32 v80, v80
	v_exp_f32_e32 v81, v81
	v_pk_add_f32 v[242:243], v[242:243], v[98:99]
	v_exp_f32_e32 v82, v82
	v_exp_f32_e32 v83, v83
	v_pk_add_f32 v[242:243], v[242:243], v[68:69]
	v_pk_add_f32 v[242:243], v[242:243], v[70:71]
	v_pk_add_f32 v[242:243], v[242:243], v[72:73]
	v_pk_add_f32 v[242:243], v[242:243], v[74:75]
	v_pk_add_f32 v[242:243], v[242:243], v[76:77]
	v_pk_add_f32 v[242:243], v[242:243], v[78:79]
	v_pk_add_f32 v[242:243], v[242:243], v[80:81]
	v_pk_add_f32 v[242:243], v[242:243], v[82:83]
	v_add_f32_e32 v241, v242, v243
	v_mov_b32_e32 v242, v241
	s_nop 1
	v_permlane32_swap_b32_e32 v241, v242
	v_cmp_gt_f32_e32 vcc, 1.0, v165
	s_cbranch_vccz .LBB0_941
	s_and_saveexec_b64 s[12:13], s[10:11]
	s_cbranch_execz .LBB0_940
	ds_write_b32 v155, v165 offset:128
	s_branch .LBB0_940
